# mixer queues: next unit index reserved one unit ahead (atomic overlaps the current unit); queue/flag words read with ds_read instead of flat loads
# baseline (speedup 1.0000x reference)
.Lmx_prio_skip:
	s_mov_b32 s100, 0
	s_add_u32 s2, s50, s7
	v_and_b32_e32 v2, 63, v0
	v_readlane_b32 s6, v255, 17
	s_addc_u32 s3, s51, s6
	v_lshlrev_b32_e32 v0, 2, v2
	v_mov_b32_e32 v1, v113
	v_lshl_add_u64 v[4:5], s[2:3], 0, v[0:1]
	s_add_u32 s2, s48, s7
	s_addc_u32 s3, s49, s6
	v_lshl_add_u64 v[6:7], s[2:3], 0, v[0:1]
	v_or_b32_e32 v3, 0xffffffc0, v2
	v_mov_b32_e32 v8, 0
	s_mov_b64 s[2:3], 0
	v_mov_b32_e32 v1, 0
	s_mov_b64 s[6:7], 0x100
	global_load_dword v9, v[6:7], off
	global_load_dword v10, v[4:5], off
	v_mov_b32_e32 v11, 0
	v_mov_b32_e32 v12, 0
	v_cmp_gt_u32_e32 vcc, 32, v2
	s_and_saveexec_b64 s[2:3], vcc
	global_load_dword v11, v[6:7], off offset:256
	global_load_dword v12, v[4:5], off offset:256
	s_or_b64 exec, exec, s[2:3]
	s_waitcnt vmcnt(0)
	v_max_f32_e64 v9, |v9|, |v9|
	v_max_f32_e32 v8, v8, v9
	v_max_f32_e64 v11, |v11|, |v11|
	v_max_f32_e32 v8, v8, v11
	v_max_f32_e64 v10, |v10|, |v10|
	v_max_f32_e32 v1, v1, v10
	v_max_f32_e64 v12, |v12|, |v12|
	v_max_f32_e32 v1, v1, v12
	s_or_b64 exec, exec, s[2:3]
	s_load_dwordx4 s[44:47], s[84:85], 0xa0
	s_load_dwordx2 s[10:11], s[84:85], 0xb0
	v_readlane_b32 s2, v254, 62
	v_sub_u32_e32 v3, 0xe87, v2
	v_lshrrev_b32_e32 v3, 6, v3
	v_or_b32_e32 v112, s2, v2
	v_lshlrev_b64 v[4:5], 2, v[112:113]
	s_waitcnt lgkmcnt(0)
	v_lshl_add_u64 v[6:7], s[44:45], 0, v[4:5]
	v_lshl_add_u64 v[4:5], s[46:47], 0, v[4:5]
	global_load_dword v7, v[6:7], off
	v_add_u32_e32 v10, 1, v3
	global_load_dword v6, v[4:5], off
	v_or_b32_e32 v3, 64, v2
	v_readlane_b32 s3, v254, 63
	s_mov_b32 s12, 2
	v_and_b32_e32 v9, 62, v10
	v_mov_b32_e32 v12, 0
	s_mov_b64 s[8:9], 0
	v_mov_b64_e32 v[4:5], v[2:3]
	v_mov_b32_e32 v3, 0
	v_readlane_b32 s13, v255, 10
	v_readlane_b32 s14, v255, 11
	s_nop 1
	v_add_u32_e32 v112, s13, v2
	v_lshl_add_u64 v[12:13], v[112:113], 2, s[10:11]
	s_mov_b64 s[98:99], 0x1000
	v_mov_b32_e32 v4, 0
	global_load_dword v16, v[12:13], off
	global_load_dword v17, v[12:13], off offset:256
	global_load_dword v18, v[12:13], off offset:512
	global_load_dword v19, v[12:13], off offset:768
	global_load_dword v20, v[12:13], off offset:1024
	global_load_dword v21, v[12:13], off offset:1280
	global_load_dword v22, v[12:13], off offset:1536
	global_load_dword v23, v[12:13], off offset:1792
	global_load_dword v24, v[12:13], off offset:2048
	global_load_dword v25, v[12:13], off offset:2304
	global_load_dword v26, v[12:13], off offset:2560
	global_load_dword v27, v[12:13], off offset:2816
	global_load_dword v28, v[12:13], off offset:3072
	global_load_dword v29, v[12:13], off offset:3328
	global_load_dword v30, v[12:13], off offset:3584
	global_load_dword v31, v[12:13], off offset:3840
	v_lshl_add_u64 v[12:13], v[12:13], 0, s[98:99]
	global_load_dword v32, v[12:13], off
	global_load_dword v33, v[12:13], off offset:256
	global_load_dword v34, v[12:13], off offset:512
	global_load_dword v35, v[12:13], off offset:768
	global_load_dword v36, v[12:13], off offset:1024
	global_load_dword v37, v[12:13], off offset:1280
	global_load_dword v38, v[12:13], off offset:1536
	global_load_dword v39, v[12:13], off offset:1792
	global_load_dword v40, v[12:13], off offset:2048
	global_load_dword v41, v[12:13], off offset:2304
	global_load_dword v42, v[12:13], off offset:2560
	global_load_dword v43, v[12:13], off offset:2816
	global_load_dword v44, v[12:13], off offset:3072
	global_load_dword v45, v[12:13], off offset:3328
	global_load_dword v46, v[12:13], off offset:3584
	global_load_dword v47, v[12:13], off offset:3840
	v_lshl_add_u64 v[12:13], v[12:13], 0, s[98:99]
	global_load_dword v48, v[12:13], off
	global_load_dword v49, v[12:13], off offset:256
	global_load_dword v50, v[12:13], off offset:512
	global_load_dword v51, v[12:13], off offset:768
	global_load_dword v52, v[12:13], off offset:1024
	global_load_dword v53, v[12:13], off offset:1280
	global_load_dword v54, v[12:13], off offset:1536
	global_load_dword v55, v[12:13], off offset:1792
	global_load_dword v56, v[12:13], off offset:2048
	global_load_dword v57, v[12:13], off offset:2304
	global_load_dword v58, v[12:13], off offset:2560
	global_load_dword v59, v[12:13], off offset:2816
	global_load_dword v60, v[12:13], off offset:3072
	global_load_dword v61, v[12:13], off offset:3328
	global_load_dword v62, v[12:13], off offset:3584
	global_load_dword v63, v[12:13], off offset:3840
	v_lshl_add_u64 v[12:13], v[12:13], 0, s[98:99]
	global_load_dword v64, v[12:13], off
	global_load_dword v65, v[12:13], off offset:256
	global_load_dword v66, v[12:13], off offset:512
	global_load_dword v67, v[12:13], off offset:768
	global_load_dword v68, v[12:13], off offset:1024
	global_load_dword v69, v[12:13], off offset:1280
	global_load_dword v70, v[12:13], off offset:1536
	global_load_dword v71, v[12:13], off offset:1792
	global_load_dword v72, v[12:13], off offset:2048
	global_load_dword v73, v[12:13], off offset:2304
	v_mov_b32_e32 v74, 0
	v_cmp_gt_u32_e32 vcc, 8, v2
	s_and_saveexec_b64 s[6:7], vcc
	global_load_dword v74, v[12:13], off offset:2560
	s_or_b64 exec, exec, s[6:7]
	s_waitcnt vmcnt(0)
	v_max_f32_e64 v16, |v16|, |v16|
	v_max_f32_e32 v4, v4, v16
	v_max_f32_e64 v17, |v17|, |v17|
	v_max_f32_e32 v4, v4, v17
	v_max_f32_e64 v18, |v18|, |v18|
	v_max_f32_e32 v4, v4, v18
	v_max_f32_e64 v19, |v19|, |v19|
	v_max_f32_e32 v4, v4, v19
	v_max_f32_e64 v20, |v20|, |v20|
	v_max_f32_e32 v4, v4, v20
	v_max_f32_e64 v21, |v21|, |v21|
	v_max_f32_e32 v4, v4, v21
	v_max_f32_e64 v22, |v22|, |v22|
	v_max_f32_e32 v4, v4, v22
	v_max_f32_e64 v23, |v23|, |v23|
	v_max_f32_e32 v4, v4, v23
	v_max_f32_e64 v24, |v24|, |v24|
	v_max_f32_e32 v4, v4, v24
	v_max_f32_e64 v25, |v25|, |v25|
	v_max_f32_e32 v4, v4, v25
	v_max_f32_e64 v26, |v26|, |v26|
	v_max_f32_e32 v4, v4, v26
	v_max_f32_e64 v27, |v27|, |v27|
	v_max_f32_e32 v4, v4, v27
	v_max_f32_e64 v28, |v28|, |v28|
	v_max_f32_e32 v4, v4, v28
	v_max_f32_e64 v29, |v29|, |v29|
	v_max_f32_e32 v4, v4, v29
	v_max_f32_e64 v30, |v30|, |v30|
	v_max_f32_e32 v4, v4, v30
	v_max_f32_e64 v31, |v31|, |v31|
	v_max_f32_e32 v4, v4, v31
	v_max_f32_e64 v32, |v32|, |v32|
	v_max_f32_e32 v4, v4, v32
	v_max_f32_e64 v33, |v33|, |v33|
	v_max_f32_e32 v4, v4, v33
	v_max_f32_e64 v34, |v34|, |v34|
	v_max_f32_e32 v4, v4, v34
	v_max_f32_e64 v35, |v35|, |v35|
	v_max_f32_e32 v4, v4, v35
	v_max_f32_e64 v36, |v36|, |v36|
	v_max_f32_e32 v4, v4, v36
	v_max_f32_e64 v37, |v37|, |v37|
	v_max_f32_e32 v4, v4, v37
	v_max_f32_e64 v38, |v38|, |v38|
	v_max_f32_e32 v4, v4, v38
	v_max_f32_e64 v39, |v39|, |v39|
	v_max_f32_e32 v4, v4, v39
	v_max_f32_e64 v40, |v40|, |v40|
	v_max_f32_e32 v4, v4, v40
	v_max_f32_e64 v41, |v41|, |v41|
	v_max_f32_e32 v4, v4, v41
	v_max_f32_e64 v42, |v42|, |v42|
	v_max_f32_e32 v4, v4, v42
	v_max_f32_e64 v43, |v43|, |v43|
	v_max_f32_e32 v4, v4, v43
	v_max_f32_e64 v44, |v44|, |v44|
	v_max_f32_e32 v4, v4, v44
	v_max_f32_e64 v45, |v45|, |v45|
	v_max_f32_e32 v4, v4, v45
	v_max_f32_e64 v46, |v46|, |v46|
	v_max_f32_e32 v4, v4, v46
	v_max_f32_e64 v47, |v47|, |v47|
	v_max_f32_e32 v4, v4, v47
	v_max_f32_e64 v48, |v48|, |v48|
	v_max_f32_e32 v4, v4, v48
	v_max_f32_e64 v49, |v49|, |v49|
	v_max_f32_e32 v4, v4, v49
	v_max_f32_e64 v50, |v50|, |v50|
	v_max_f32_e32 v4, v4, v50
	v_max_f32_e64 v51, |v51|, |v51|
	v_max_f32_e32 v4, v4, v51
	v_max_f32_e64 v52, |v52|, |v52|
	v_max_f32_e32 v4, v4, v52
	v_max_f32_e64 v53, |v53|, |v53|
	v_max_f32_e32 v4, v4, v53
	v_max_f32_e64 v54, |v54|, |v54|
	v_max_f32_e32 v4, v4, v54
	v_max_f32_e64 v55, |v55|, |v55|
	v_max_f32_e32 v4, v4, v55
	v_max_f32_e64 v56, |v56|, |v56|
	v_max_f32_e32 v4, v4, v56
	v_max_f32_e64 v57, |v57|, |v57|
	v_max_f32_e32 v4, v4, v57
	v_max_f32_e64 v58, |v58|, |v58|
	v_max_f32_e32 v4, v4, v58
	v_max_f32_e64 v59, |v59|, |v59|
	v_max_f32_e32 v4, v4, v59
	v_max_f32_e64 v60, |v60|, |v60|
	v_max_f32_e32 v4, v4, v60
	v_max_f32_e64 v61, |v61|, |v61|
	v_max_f32_e32 v4, v4, v61
	v_max_f32_e64 v62, |v62|, |v62|
	v_max_f32_e32 v4, v4, v62
	v_max_f32_e64 v63, |v63|, |v63|
	v_max_f32_e32 v4, v4, v63
	v_max_f32_e64 v64, |v64|, |v64|
	v_max_f32_e32 v4, v4, v64
	v_max_f32_e64 v65, |v65|, |v65|
	v_max_f32_e32 v4, v4, v65
	v_max_f32_e64 v66, |v66|, |v66|
	v_max_f32_e32 v4, v4, v66
	v_max_f32_e64 v67, |v67|, |v67|
	v_max_f32_e32 v4, v4, v67
	v_max_f32_e64 v68, |v68|, |v68|
	v_max_f32_e32 v4, v4, v68
	v_max_f32_e64 v69, |v69|, |v69|
	v_max_f32_e32 v4, v4, v69
	v_max_f32_e64 v70, |v70|, |v70|
	v_max_f32_e32 v4, v4, v70
	v_max_f32_e64 v71, |v71|, |v71|
	v_max_f32_e32 v4, v4, v71
	v_max_f32_e64 v72, |v72|, |v72|
	v_max_f32_e32 v4, v4, v72
	v_max_f32_e64 v73, |v73|, |v73|
	v_max_f32_e32 v4, v4, v73
	v_max_f32_e64 v74, |v74|, |v74|
	v_max_f32_e32 v4, v4, v74

.LBB0_1015:
	s_and_saveexec_b64 s[2:3], s[4:5]
	s_cbranch_execz .LBB0_1017
	v_mov_b64_e32 v[0:1], s[48:49]
	s_cmp_eq_u32 s100, 1
	s_cbranch_scc0 .Lmx_tk_fresh
	s_waitcnt vmcnt(0)
	v_mov_b32_e32 v2, v240
	s_branch .Lmx_tk_got
.Lmx_tk_fresh:
	flat_atomic_add v2, v[0:1], v196 offset:4 sc0
	s_waitcnt vmcnt(0) lgkmcnt(0)
.Lmx_tk_got:
	s_mov_b32 s100, 0
	v_cmp_gt_i32_e32 vcc, s76, v2
	s_cbranch_vccz .Lmx_tk_nopf
	flat_atomic_add v240, v[0:1], v196 offset:4 sc0
	s_mov_b32 s100, 1
.Lmx_tk_nopf:
	v_mov_b32_e32 v0, 0x222e0
	ds_write_b32 v0, v2
.LBB0_1017:
	s_or_b64 exec, exec, s[2:3]
	s_add_i32 s2, 0, 0x222e0
	s_cmp_lg_u32 s2, -1
	s_cselect_b32 s2, s2, 0
	s_cselect_b32 s3, s23, 0
	v_mov_b32_e32 v0, s2
	v_mov_b32_e32 v1, s3
	s_waitcnt lgkmcnt(0)
	s_barrier
	v_mov_b32_e32 v0, 0x222e0
	ds_read_b32 v9, v0
	s_waitcnt lgkmcnt(0)
	s_mov_b64 s[2:3], -1
	s_waitcnt lgkmcnt(0)
	s_barrier
	v_cmp_gt_i32_e32 vcc, s76, v9
	s_and_saveexec_b64 s[60:61], vcc
	s_cbranch_execz .LBB0_1014
	s_add_i32 s2, 0, 0x22318
	s_cmp_lg_u32 s2, -1
	s_cselect_b32 s2, s2, 0
	s_cselect_b32 s3, s23, 0
	v_mov_b32_e32 v0, s2
	v_mov_b32_e32 v1, s3
	v_mov_b32_e32 v0, 0x22318
	ds_read_b32 v0, v0
	s_waitcnt lgkmcnt(0)
	v_and_b32_e32 v1, 0x7ffffffc, v9
	s_movk_i32 s2, 0x80
	v_cmp_lt_i32_e64 s[46:47], 63, v9
	v_cmp_ne_u32_e32 vcc, s2, v1
	s_and_b64 s[2:3], s[46:47], vcc
	s_waitcnt lgkmcnt(0)
	v_cmp_eq_f32_e64 s[44:45], 0, v0
	s_and_saveexec_b64 s[6:7], s[2:3]
	s_xor_b64 s[62:63], exec, s[6:7]
	s_cbranch_execz .LBB0_1146
	s_add_i32 s2, 0, 0x22314
	s_cmp_lg_u32 s2, -1
	s_cselect_b32 s2, s2, 0
	s_cselect_b32 s3, s23, 0
	v_mov_b32_e32 v0, s2
	v_mov_b32_e32 v1, s3
	v_mov_b32_e32 v0, 0x22314
	ds_read_b32 v16, v0
	s_waitcnt lgkmcnt(0)
	s_movk_i32 s2, 0x7f
	v_cmp_lt_u32_e32 vcc, s2, v9
	s_and_saveexec_b64 s[2:3], vcc
	s_xor_b64 s[2:3], exec, s[2:3]
	s_cbranch_execz .LBB0_1021
	v_lshl_add_u32 v4, v9, 8, v247
	v_mov_b64_e32 v[2:3], s[30:31]
	v_mad_u64_u32 v[0:1], s[6:7], v4, s33, 0
	v_mad_u64_u32 v[2:3], s[6:7], v4, s33, v[2:3]
	s_lshl_b32 s34, s81, 1
	v_lshl_add_u64 v[2:3], v[2:3], 0, s[34:35]
	s_mov_b64 s[6:7], 0x1000
	v_lshl_add_u64 v[138:139], v[2:3], 0, s[6:7]
	s_mov_b64 s[6:7], 0x1400
	v_lshl_add_u64 v[140:141], v[2:3], 0, s[6:7]

.LBB0_1151:
	s_or_b64 exec, exec, s[2:3]
	v_mov_b64_e32 v[6:7], s[30:31]
	v_mad_u64_u32 v[6:7], s[2:3], v4, s33, v[6:7]
	v_mov_b32_e32 v4, v7
	v_mad_u64_u32 v[4:5], s[2:3], v5, s33, v[4:5]
	v_mov_b32_e32 v7, v4
	s_lshl_b32 s34, s81, 1
	v_lshl_add_u64 v[4:5], v[6:7], 0, s[34:35]
	s_mov_b64 s[2:3], 0x1800
	v_lshl_add_u64 v[144:145], v[4:5], 0, s[2:3]
	s_mov_b32 s6, 0x88000
	v_mov_b64_e32 v[4:5], s[54:55]
	v_mul_lo_u32 v6, v3, s6
	v_mad_u64_u32 v[8:9], s[2:3], v2, s6, 0
	v_mad_u64_u32 v[12:13], s[2:3], v2, s6, v[4:5]
	s_mov_b32 s6, 0xcc000
	v_mov_b64_e32 v[4:5], s[52:53]
	v_mad_u64_u32 v[10:11], s[2:3], v2, s6, 0
	v_mad_u64_u32 v[14:15], s[2:3], v2, s6, v[4:5]
	s_add_i32 s2, 0, 0x22310
	s_cmp_lg_u32 s2, -1
	v_mul_lo_u32 v3, v3, s6
	s_cselect_b32 s2, s2, 0
	s_cselect_b32 s3, s23, 0
	v_add_u32_e32 v11, v11, v3
	v_add_u32_e32 v15, v3, v15
	v_mov_b32_e32 v2, s2
	v_mov_b32_e32 v3, s3
	v_mov_b32_e32 v2, 0x22310
	ds_read_b32 v28, v2
	s_waitcnt lgkmcnt(0)
	v_add_u32_e32 v9, v9, v6
	v_add_u32_e32 v13, v6, v13
	s_and_saveexec_b64 s[2:3], s[44:45]
	s_xor_b64 s[44:45], exec, s[2:3]
	s_cbranch_execz .LBB0_1173
	s_waitcnt lgkmcnt(0)
	v_mov_b32_e32 v28, v246
	v_mov_b32_e32 v21, v113
	v_ashrrev_i32_e32 v2, 1, v28
	v_bfe_u32 v29, v28, 5, 1
	v_bfi_b32 v164, s92, v2, v28
	v_mad_i64_i32 v[0:1], s[2:3], v164, s22, v[0:1]
	v_lshlrev_b32_e32 v20, 4, v29
	v_lshl_add_u64 v[0:1], v[0:1], 0, v[20:21]
	s_mov_b32 s6, 0x2aaaaaab
	global_load_dwordx4 v[124:127], v[0:1], off
	global_load_dwordx4 v[120:123], v[0:1], off offset:32
	global_load_dwordx4 v[116:119], v[0:1], off offset:64
	global_load_dwordx4 v[106:109], v[0:1], off offset:96
	global_load_dwordx4 v[102:105], v[0:1], off offset:128
	global_load_dwordx4 v[98:101], v[0:1], off offset:160
	v_mul_hi_i32 v0, v28, s6
	v_lshrrev_b32_e32 v1, 31, v0
	v_ashrrev_i32_e32 v0, 1, v0
	v_add_u32_e32 v21, v0, v1
	v_mul_lo_u32 v0, v21, 12
	v_sub_u32_e32 v32, v28, v0
	s_movk_i32 s2, 0x60
	v_mad_i64_i32 v[26:27], s[2:3], v21, s2, 0
	v_lshlrev_b32_e32 v16, 3, v32
	v_lshl_add_u64 v[0:1], v[26:27], 1, v[14:15]
	v_ashrrev_i32_e32 v17, 31, v16
	v_lshl_add_u64 v[0:1], v[16:17], 1, v[0:1]
	global_load_dwordx4 v[0:3], v[0:1], off
	v_add_u32_e32 v4, 0x200, v28
	v_mul_hi_i32 v5, v4, s6
	v_lshrrev_b32_e32 v6, 31, v5
	v_ashrrev_i32_e32 v5, 1, v5
	v_add_u32_e32 v30, v5, v6
	v_mul_lo_u32 v5, v30, 12
	v_sub_u32_e32 v33, v4, v5
	v_mov_b32_e32 v114, v113
	v_mov_b32_e32 v115, v113
	s_movk_i32 s2, 0x100
	v_mov_b32_e32 v112, v113
	v_lshlrev_b32_e32 v18, 3, v33
	v_mov_b64_e32 v[130:131], v[114:115]
	v_cmp_lt_i32_e32 vcc, s90, v28
	v_cmp_gt_i32_e64 s[6:7], s2, v28
	v_ashrrev_i32_e32 v19, 31, v18
	v_mov_b64_e32 v[128:129], v[112:113]
	s_and_saveexec_b64 s[2:3], s[6:7]
	s_cbranch_execz .LBB0_1154
	v_mad_i64_i32 v[4:5], s[18:19], v30, s22, v[14:15]
	v_lshl_add_u64 v[4:5], v[18:19], 1, v[4:5]
	global_load_dwordx4 v[128:131], v[4:5], off
